# speedup vs baseline: 1.0123x; 1.0068x over previous
; __device__ __forceinline__ unsigned cvtpk(float lo, float hi) { unsigned r; asm volatile("v_cvt_pk_bf16_f32 %0, %1, %2" : "=v"(r) : "v"(lo), "v"(hi)); return r; }
;     __device__ __forceinline__ void operator()(const AccT& acc, const pg8::Unit& u, int wr, int wc, int fr, int fq, pg8::RsCache& rsc) const {
;     ...
; #pragma unroll
;         for (int ai = 0; ai < 2; ++ai) {
; #pragma unroll
;             for (int m = 0; m < 4; ++m) {
;                 const int row = row0 + ai * 128 + m * 16;
;                 const float rs = rsc.rl[ai * 64 + m * 16 + fr], rsn = rs * -1.4426950408889634f, rs2 = rs * rs;
;                 float hv[8];
; #pragma unroll
;                 for (int n = 0; n < 2; ++n) {
;                     const f32x4 gq = acc[ai][0][m][n], t = gq * acc[ai][1][m][n] * rs2, ea = gq * rsn;
; #pragma unroll
;                     for (int j = 0; j < 4; ++j) hv[n * 4 + j] = t[j] * __builtin_amdgcn_rcpf(1.0f + __builtin_amdgcn_exp2f(ea[j]));
;                 }
;                 u32x4 w; w.x = cvtpk(hv[0], hv[1]); w.y = cvtpk(hv[2], hv[3]); w.z = cvtpk(hv[4], hv[5]); w.w = cvtpk(hv[6], hv[7]);
;                 *(u32x4*)(H + (size_t)row * DFF + col0) = w;
;             }
.LBB0_444:
	v_lshl_or_b32 v132, s55, 7, v157
	v_ashrrev_i32_e32 v133, 31, v132
	s_and_b64 vcc, exec, s[6:7]
	s_mov_b32 s56, s51
	ds_read_b32 v240, v156
	ds_read_b32 v241, v156 offset:64
	ds_read_b32 v243, v156 offset:128
	ds_read_b32 v244, v156 offset:192
	ds_read_b32 v245, v156 offset:256
	ds_read_b32 v246, v156 offset:320
	ds_read_b32 v247, v156 offset:384
	ds_read_b32 v248, v156 offset:448
	s_mov_b32 s55, s10
	s_mov_b64 s[24:25], s[16:17]
	s_mov_b64 s[36:37], s[14:15]
	v_mov_b64_e32 v[216:217], s[8:9]
	v_lshlrev_b64 v[218:219], 1, v[132:133]
	v_mov_b32_e32 v234, 1.0
	v_mov_b32_e32 v235, 1.0
	s_waitcnt lgkmcnt(0)
	v_mul_f32_e32 v222, 0xbfb8aa3b, v240
	v_mul_f32_e32 v224, v240, v240
	v_pk_mul_f32 v[226:227], v[126:127], v[222:223] op_sel_hi:[1,0]
	v_pk_mul_f32 v[228:229], v[128:129], v[222:223] op_sel_hi:[1,0]
	v_pk_mul_f32 v[230:231], v[118:119], v[222:223] op_sel_hi:[1,0]
	v_pk_mul_f32 v[232:233], v[120:121], v[222:223] op_sel_hi:[1,0]
	v_pk_mul_f32 v[126:127], v[126:127], v[122:123]
	v_pk_mul_f32 v[128:129], v[128:129], v[124:125]
	v_pk_mul_f32 v[118:119], v[118:119], v[114:115]
	v_pk_mul_f32 v[120:121], v[120:121], v[116:117]
	v_exp_f32_e32 v226, v226
	v_exp_f32_e32 v227, v227
	v_exp_f32_e32 v228, v228
	v_exp_f32_e32 v229, v229
	v_exp_f32_e32 v230, v230
	v_exp_f32_e32 v231, v231
	v_exp_f32_e32 v232, v232
	v_exp_f32_e32 v233, v233
	v_pk_mul_f32 v[126:127], v[126:127], v[224:225] op_sel_hi:[1,0]
	v_pk_mul_f32 v[128:129], v[128:129], v[224:225] op_sel_hi:[1,0]
	v_pk_mul_f32 v[118:119], v[118:119], v[224:225] op_sel_hi:[1,0]
	v_pk_mul_f32 v[120:121], v[120:121], v[224:225] op_sel_hi:[1,0]
	v_pk_add_f32 v[226:227], v[226:227], v[234:235]
	v_pk_add_f32 v[228:229], v[228:229], v[234:235]
	v_pk_add_f32 v[230:231], v[230:231], v[234:235]
	v_pk_add_f32 v[232:233], v[232:233], v[234:235]
	v_rcp_f32_e32 v226, v226
	v_rcp_f32_e32 v227, v227
	v_rcp_f32_e32 v228, v228
	v_rcp_f32_e32 v229, v229
	v_rcp_f32_e32 v230, v230
	v_rcp_f32_e32 v231, v231
	v_rcp_f32_e32 v232, v232
	v_rcp_f32_e32 v233, v233
	v_mad_i64_i32 v[220:221], s[22:23], v150, s90, v[216:217]
	v_pk_mul_f32 v[126:127], v[126:127], v[226:227]
	v_pk_mul_f32 v[128:129], v[128:129], v[228:229]
	v_pk_mul_f32 v[118:119], v[118:119], v[230:231]
	v_pk_mul_f32 v[120:121], v[120:121], v[232:233]
	v_lshl_add_u64 v[220:221], v[220:221], 0, v[218:219]
	v_cvt_pk_bf16_f32 v236, v126, v127
	v_cvt_pk_bf16_f32 v237, v128, v129
	v_cvt_pk_bf16_f32 v238, v118, v119
	v_cvt_pk_bf16_f32 v239, v120, v121
	global_store_dwordx4 v[220:221], v[236:239], off
	v_mul_f32_e32 v222, 0xbfb8aa3b, v241
	v_mul_f32_e32 v224, v241, v241
	v_pk_mul_f32 v[226:227], v[110:111], v[222:223] op_sel_hi:[1,0]
	v_pk_mul_f32 v[228:229], v[112:113], v[222:223] op_sel_hi:[1,0]
	v_pk_mul_f32 v[230:231], v[102:103], v[222:223] op_sel_hi:[1,0]
	v_pk_mul_f32 v[232:233], v[104:105], v[222:223] op_sel_hi:[1,0]
	v_pk_mul_f32 v[110:111], v[110:111], v[106:107]
	v_pk_mul_f32 v[112:113], v[112:113], v[108:109]
	v_pk_mul_f32 v[102:103], v[102:103], v[98:99]
	v_pk_mul_f32 v[104:105], v[104:105], v[100:101]
	v_exp_f32_e32 v226, v226
	v_exp_f32_e32 v227, v227
	v_exp_f32_e32 v228, v228
	v_exp_f32_e32 v229, v229
	v_exp_f32_e32 v230, v230
	v_exp_f32_e32 v231, v231
	v_exp_f32_e32 v232, v232
	v_exp_f32_e32 v233, v233
	v_pk_mul_f32 v[110:111], v[110:111], v[224:225] op_sel_hi:[1,0]
	v_pk_mul_f32 v[112:113], v[112:113], v[224:225] op_sel_hi:[1,0]
	v_pk_mul_f32 v[102:103], v[102:103], v[224:225] op_sel_hi:[1,0]
	v_pk_mul_f32 v[104:105], v[104:105], v[224:225] op_sel_hi:[1,0]
	v_pk_add_f32 v[226:227], v[226:227], v[234:235]
	v_pk_add_f32 v[228:229], v[228:229], v[234:235]
	v_pk_add_f32 v[230:231], v[230:231], v[234:235]
	v_pk_add_f32 v[232:233], v[232:233], v[234:235]
	v_rcp_f32_e32 v226, v226
	v_rcp_f32_e32 v227, v227
	v_rcp_f32_e32 v228, v228
	v_rcp_f32_e32 v229, v229
	v_rcp_f32_e32 v230, v230
	v_rcp_f32_e32 v231, v231
	v_rcp_f32_e32 v232, v232
	v_rcp_f32_e32 v233, v233
	v_mad_i64_i32 v[220:221], s[22:23], v148, s90, v[216:217]
	v_pk_mul_f32 v[110:111], v[110:111], v[226:227]
	v_pk_mul_f32 v[112:113], v[112:113], v[228:229]
	v_pk_mul_f32 v[102:103], v[102:103], v[230:231]
	v_pk_mul_f32 v[104:105], v[104:105], v[232:233]
	v_lshl_add_u64 v[220:221], v[220:221], 0, v[218:219]
	v_cvt_pk_bf16_f32 v236, v110, v111
	v_cvt_pk_bf16_f32 v237, v112, v113
	v_cvt_pk_bf16_f32 v238, v102, v103
	v_cvt_pk_bf16_f32 v239, v104, v105
	global_store_dwordx4 v[220:221], v[236:239], off
	v_mul_f32_e32 v222, 0xbfb8aa3b, v243
	v_mul_f32_e32 v224, v243, v243
	v_pk_mul_f32 v[226:227], v[94:95], v[222:223] op_sel_hi:[1,0]
	v_pk_mul_f32 v[228:229], v[96:97], v[222:223] op_sel_hi:[1,0]
	v_pk_mul_f32 v[230:231], v[86:87], v[222:223] op_sel_hi:[1,0]
	v_pk_mul_f32 v[232:233], v[88:89], v[222:223] op_sel_hi:[1,0]
	v_pk_mul_f32 v[94:95], v[94:95], v[90:91]
	v_pk_mul_f32 v[96:97], v[96:97], v[92:93]
	v_pk_mul_f32 v[86:87], v[86:87], v[82:83]
	v_pk_mul_f32 v[88:89], v[88:89], v[84:85]
	v_exp_f32_e32 v226, v226
	v_exp_f32_e32 v227, v227
	v_exp_f32_e32 v228, v228
	v_exp_f32_e32 v229, v229
	v_exp_f32_e32 v230, v230
	v_exp_f32_e32 v231, v231
	v_exp_f32_e32 v232, v232
	v_exp_f32_e32 v233, v233
	v_pk_mul_f32 v[94:95], v[94:95], v[224:225] op_sel_hi:[1,0]
	v_pk_mul_f32 v[96:97], v[96:97], v[224:225] op_sel_hi:[1,0]
	v_pk_mul_f32 v[86:87], v[86:87], v[224:225] op_sel_hi:[1,0]
	v_pk_mul_f32 v[88:89], v[88:89], v[224:225] op_sel_hi:[1,0]
	v_pk_add_f32 v[226:227], v[226:227], v[234:235]
	v_pk_add_f32 v[228:229], v[228:229], v[234:235]
	v_pk_add_f32 v[230:231], v[230:231], v[234:235]
	v_pk_add_f32 v[232:233], v[232:233], v[234:235]
	v_rcp_f32_e32 v226, v226
	v_rcp_f32_e32 v227, v227
	v_rcp_f32_e32 v228, v228
; __device__ __forceinline__ unsigned cvtpk(float lo, float hi) { unsigned r; asm volatile("v_cvt_pk_bf16_f32 %0, %1, %2" : "=v"(r) : "v"(lo), "v"(hi)); return r; }
;     __device__ __forceinline__ void operator()(const AccT& acc, const pg8::Unit& u, int wr, int wc, int fr, int fq, pg8::RsCache& rsc) const {
;     ...
; #pragma unroll
;         for (int ai = 0; ai < 2; ++ai) {
; #pragma unroll
;             for (int m = 0; m < 4; ++m) {
;                 const int row = row0 + ai * 128 + m * 16;
;                 const float rs = rsc.rl[ai * 64 + m * 16 + fr], rsn = rs * -1.4426950408889634f, rs2 = rs * rs;
;                 float hv[8];
; #pragma unroll
;                 for (int n = 0; n < 2; ++n) {
;                     const f32x4 gq = acc[ai][0][m][n], t = gq * acc[ai][1][m][n] * rs2, ea = gq * rsn;
; #pragma unroll
;                     for (int j = 0; j < 4; ++j) hv[n * 4 + j] = t[j] * __builtin_amdgcn_rcpf(1.0f + __builtin_amdgcn_exp2f(ea[j]));
;                 }
;                 u32x4 w; w.x = cvtpk(hv[0], hv[1]); w.y = cvtpk(hv[2], hv[3]); w.z = cvtpk(hv[4], hv[5]); w.w = cvtpk(hv[6], hv[7]);
;                 *(u32x4*)(H + (size_t)row * DFF + col0) = w;
;             }
	v_rcp_f32_e32 v229, v229
	v_rcp_f32_e32 v230, v230
	v_rcp_f32_e32 v231, v231
	v_rcp_f32_e32 v232, v232
	v_rcp_f32_e32 v233, v233
	v_mad_i64_i32 v[220:221], s[22:23], v146, s90, v[216:217]
	v_pk_mul_f32 v[94:95], v[94:95], v[226:227]
	v_pk_mul_f32 v[96:97], v[96:97], v[228:229]
	v_pk_mul_f32 v[86:87], v[86:87], v[230:231]
	v_pk_mul_f32 v[88:89], v[88:89], v[232:233]
	v_lshl_add_u64 v[220:221], v[220:221], 0, v[218:219]
	v_cvt_pk_bf16_f32 v236, v94, v95
	v_cvt_pk_bf16_f32 v237, v96, v97
	v_cvt_pk_bf16_f32 v238, v86, v87
	v_cvt_pk_bf16_f32 v239, v88, v89
	global_store_dwordx4 v[220:221], v[236:239], off
	v_mul_f32_e32 v222, 0xbfb8aa3b, v244
	v_mul_f32_e32 v224, v244, v244
	v_pk_mul_f32 v[226:227], v[78:79], v[222:223] op_sel_hi:[1,0]
	v_pk_mul_f32 v[228:229], v[80:81], v[222:223] op_sel_hi:[1,0]
	v_pk_mul_f32 v[230:231], v[70:71], v[222:223] op_sel_hi:[1,0]
	v_pk_mul_f32 v[232:233], v[72:73], v[222:223] op_sel_hi:[1,0]
	v_pk_mul_f32 v[78:79], v[78:79], v[74:75]
	v_pk_mul_f32 v[80:81], v[80:81], v[76:77]
	v_pk_mul_f32 v[70:71], v[70:71], v[66:67]
	v_pk_mul_f32 v[72:73], v[72:73], v[68:69]
	v_exp_f32_e32 v226, v226
	v_exp_f32_e32 v227, v227
	v_exp_f32_e32 v228, v228
	v_exp_f32_e32 v229, v229
	v_exp_f32_e32 v230, v230
	v_exp_f32_e32 v231, v231
	v_exp_f32_e32 v232, v232
	v_exp_f32_e32 v233, v233
	v_pk_mul_f32 v[78:79], v[78:79], v[224:225] op_sel_hi:[1,0]
	v_pk_mul_f32 v[80:81], v[80:81], v[224:225] op_sel_hi:[1,0]
	v_pk_mul_f32 v[70:71], v[70:71], v[224:225] op_sel_hi:[1,0]
	v_pk_mul_f32 v[72:73], v[72:73], v[224:225] op_sel_hi:[1,0]
	v_pk_add_f32 v[226:227], v[226:227], v[234:235]
	v_pk_add_f32 v[228:229], v[228:229], v[234:235]
	v_pk_add_f32 v[230:231], v[230:231], v[234:235]
	v_pk_add_f32 v[232:233], v[232:233], v[234:235]
	v_rcp_f32_e32 v226, v226
	v_rcp_f32_e32 v227, v227
	v_rcp_f32_e32 v228, v228
	v_rcp_f32_e32 v229, v229
	v_rcp_f32_e32 v230, v230
	v_rcp_f32_e32 v231, v231
	v_rcp_f32_e32 v232, v232
	v_rcp_f32_e32 v233, v233
	v_mad_i64_i32 v[220:221], s[22:23], v144, s90, v[216:217]
	v_pk_mul_f32 v[78:79], v[78:79], v[226:227]
	v_pk_mul_f32 v[80:81], v[80:81], v[228:229]
	v_pk_mul_f32 v[70:71], v[70:71], v[230:231]
	v_pk_mul_f32 v[72:73], v[72:73], v[232:233]
	v_lshl_add_u64 v[220:221], v[220:221], 0, v[218:219]
	v_cvt_pk_bf16_f32 v236, v78, v79
	v_cvt_pk_bf16_f32 v237, v80, v81
	v_cvt_pk_bf16_f32 v238, v70, v71
	v_cvt_pk_bf16_f32 v239, v72, v73
	global_store_dwordx4 v[220:221], v[236:239], off
	v_mul_f32_e32 v222, 0xbfb8aa3b, v245
	v_mul_f32_e32 v224, v245, v245
	v_pk_mul_f32 v[226:227], v[62:63], v[222:223] op_sel_hi:[1,0]
	v_pk_mul_f32 v[228:229], v[64:65], v[222:223] op_sel_hi:[1,0]
	v_pk_mul_f32 v[230:231], v[54:55], v[222:223] op_sel_hi:[1,0]
	v_pk_mul_f32 v[232:233], v[56:57], v[222:223] op_sel_hi:[1,0]
	v_pk_mul_f32 v[62:63], v[62:63], v[58:59]
	v_pk_mul_f32 v[64:65], v[64:65], v[60:61]
	v_pk_mul_f32 v[54:55], v[54:55], v[50:51]
	v_pk_mul_f32 v[56:57], v[56:57], v[52:53]
	v_exp_f32_e32 v226, v226
	v_exp_f32_e32 v227, v227
	v_exp_f32_e32 v228, v228
	v_exp_f32_e32 v229, v229
	v_exp_f32_e32 v230, v230
	v_exp_f32_e32 v231, v231
	v_exp_f32_e32 v232, v232
	v_exp_f32_e32 v233, v233
	v_pk_mul_f32 v[62:63], v[62:63], v[224:225] op_sel_hi:[1,0]
	v_pk_mul_f32 v[64:65], v[64:65], v[224:225] op_sel_hi:[1,0]
	v_pk_mul_f32 v[54:55], v[54:55], v[224:225] op_sel_hi:[1,0]
	v_pk_mul_f32 v[56:57], v[56:57], v[224:225] op_sel_hi:[1,0]
	v_pk_add_f32 v[226:227], v[226:227], v[234:235]
	v_pk_add_f32 v[228:229], v[228:229], v[234:235]
	v_pk_add_f32 v[230:231], v[230:231], v[234:235]
	v_pk_add_f32 v[232:233], v[232:233], v[234:235]
	v_rcp_f32_e32 v226, v226
	v_rcp_f32_e32 v227, v227
	v_rcp_f32_e32 v228, v228
	v_rcp_f32_e32 v229, v229
	v_rcp_f32_e32 v230, v230
	v_rcp_f32_e32 v231, v231
	v_rcp_f32_e32 v232, v232
	v_rcp_f32_e32 v233, v233
	v_mad_i64_i32 v[220:221], s[22:23], v142, s90, v[216:217]
	v_pk_mul_f32 v[62:63], v[62:63], v[226:227]
	v_pk_mul_f32 v[64:65], v[64:65], v[228:229]
	v_pk_mul_f32 v[54:55], v[54:55], v[230:231]
	v_pk_mul_f32 v[56:57], v[56:57], v[232:233]
	v_lshl_add_u64 v[220:221], v[220:221], 0, v[218:219]
	v_cvt_pk_bf16_f32 v236, v62, v63
	v_cvt_pk_bf16_f32 v237, v64, v65
	v_cvt_pk_bf16_f32 v238, v54, v55
	v_cvt_pk_bf16_f32 v239, v56, v57
	global_store_dwordx4 v[220:221], v[236:239], off
	v_mul_f32_e32 v222, 0xbfb8aa3b, v246
	v_mul_f32_e32 v224, v246, v246
	v_pk_mul_f32 v[226:227], v[46:47], v[222:223] op_sel_hi:[1,0]
	v_pk_mul_f32 v[228:229], v[48:49], v[222:223] op_sel_hi:[1,0]
	v_pk_mul_f32 v[230:231], v[38:39], v[222:223] op_sel_hi:[1,0]
	v_pk_mul_f32 v[232:233], v[40:41], v[222:223] op_sel_hi:[1,0]
	v_pk_mul_f32 v[46:47], v[46:47], v[42:43]
	v_pk_mul_f32 v[48:49], v[48:49], v[44:45]
	v_pk_mul_f32 v[38:39], v[38:39], v[34:35]
	v_pk_mul_f32 v[40:41], v[40:41], v[36:37]
	v_exp_f32_e32 v226, v226
	v_exp_f32_e32 v227, v227
	v_exp_f32_e32 v228, v228
	v_exp_f32_e32 v229, v229
	v_exp_f32_e32 v230, v230
	v_exp_f32_e32 v231, v231
; __device__ __forceinline__ unsigned cvtpk(float lo, float hi) { unsigned r; asm volatile("v_cvt_pk_bf16_f32 %0, %1, %2" : "=v"(r) : "v"(lo), "v"(hi)); return r; }
;     __device__ __forceinline__ void operator()(const AccT& acc, const pg8::Unit& u, int wr, int wc, int fr, int fq, pg8::RsCache& rsc) const {
;     ...
; #pragma unroll
;         for (int ai = 0; ai < 2; ++ai) {
; #pragma unroll
;             for (int m = 0; m < 4; ++m) {
;                 const int row = row0 + ai * 128 + m * 16;
;                 const float rs = rsc.rl[ai * 64 + m * 16 + fr], rsn = rs * -1.4426950408889634f, rs2 = rs * rs;
;                 float hv[8];
; #pragma unroll
;                 for (int n = 0; n < 2; ++n) {
;                     const f32x4 gq = acc[ai][0][m][n], t = gq * acc[ai][1][m][n] * rs2, ea = gq * rsn;
; #pragma unroll
;                     for (int j = 0; j < 4; ++j) hv[n * 4 + j] = t[j] * __builtin_amdgcn_rcpf(1.0f + __builtin_amdgcn_exp2f(ea[j]));
;                 }
;                 u32x4 w; w.x = cvtpk(hv[0], hv[1]); w.y = cvtpk(hv[2], hv[3]); w.z = cvtpk(hv[4], hv[5]); w.w = cvtpk(hv[6], hv[7]);
;                 *(u32x4*)(H + (size_t)row * DFF + col0) = w;
;             }
	v_exp_f32_e32 v232, v232
	v_exp_f32_e32 v233, v233
	v_pk_mul_f32 v[46:47], v[46:47], v[224:225] op_sel_hi:[1,0]
	v_pk_mul_f32 v[48:49], v[48:49], v[224:225] op_sel_hi:[1,0]
	v_pk_mul_f32 v[38:39], v[38:39], v[224:225] op_sel_hi:[1,0]
	v_pk_mul_f32 v[40:41], v[40:41], v[224:225] op_sel_hi:[1,0]
	v_pk_add_f32 v[226:227], v[226:227], v[234:235]
	v_pk_add_f32 v[228:229], v[228:229], v[234:235]
	v_pk_add_f32 v[230:231], v[230:231], v[234:235]
	v_pk_add_f32 v[232:233], v[232:233], v[234:235]
	v_rcp_f32_e32 v226, v226
	v_rcp_f32_e32 v227, v227
	v_rcp_f32_e32 v228, v228
	v_rcp_f32_e32 v229, v229
	v_rcp_f32_e32 v230, v230
	v_rcp_f32_e32 v231, v231
	v_rcp_f32_e32 v232, v232
	v_rcp_f32_e32 v233, v233
	v_add_u32_e32 v249, 16, v142
	v_mad_i64_i32 v[220:221], s[22:23], v249, s90, v[216:217]
	v_pk_mul_f32 v[46:47], v[46:47], v[226:227]
	v_pk_mul_f32 v[48:49], v[48:49], v[228:229]
	v_pk_mul_f32 v[38:39], v[38:39], v[230:231]
	v_pk_mul_f32 v[40:41], v[40:41], v[232:233]
	v_lshl_add_u64 v[220:221], v[220:221], 0, v[218:219]
	v_cvt_pk_bf16_f32 v236, v46, v47
	v_cvt_pk_bf16_f32 v237, v48, v49
	v_cvt_pk_bf16_f32 v238, v38, v39
	v_cvt_pk_bf16_f32 v239, v40, v41
	global_store_dwordx4 v[220:221], v[236:239], off
	v_mul_f32_e32 v222, 0xbfb8aa3b, v247
	v_mul_f32_e32 v224, v247, v247
	v_pk_mul_f32 v[226:227], v[30:31], v[222:223] op_sel_hi:[1,0]
	v_pk_mul_f32 v[228:229], v[32:33], v[222:223] op_sel_hi:[1,0]
	v_pk_mul_f32 v[230:231], v[22:23], v[222:223] op_sel_hi:[1,0]
	v_pk_mul_f32 v[232:233], v[24:25], v[222:223] op_sel_hi:[1,0]
	v_pk_mul_f32 v[30:31], v[30:31], v[26:27]
	v_pk_mul_f32 v[32:33], v[32:33], v[28:29]
	v_pk_mul_f32 v[22:23], v[22:23], v[18:19]
	v_pk_mul_f32 v[24:25], v[24:25], v[20:21]
	v_exp_f32_e32 v226, v226
	v_exp_f32_e32 v227, v227
	v_exp_f32_e32 v228, v228
	v_exp_f32_e32 v229, v229
	v_exp_f32_e32 v230, v230
	v_exp_f32_e32 v231, v231
	v_exp_f32_e32 v232, v232
	v_exp_f32_e32 v233, v233
	v_pk_mul_f32 v[30:31], v[30:31], v[224:225] op_sel_hi:[1,0]
	v_pk_mul_f32 v[32:33], v[32:33], v[224:225] op_sel_hi:[1,0]
	v_pk_mul_f32 v[22:23], v[22:23], v[224:225] op_sel_hi:[1,0]
	v_pk_mul_f32 v[24:25], v[24:25], v[224:225] op_sel_hi:[1,0]
	v_pk_add_f32 v[226:227], v[226:227], v[234:235]
	v_pk_add_f32 v[228:229], v[228:229], v[234:235]
	v_pk_add_f32 v[230:231], v[230:231], v[234:235]
	v_pk_add_f32 v[232:233], v[232:233], v[234:235]
	v_rcp_f32_e32 v226, v226
	v_rcp_f32_e32 v227, v227
	v_rcp_f32_e32 v228, v228
	v_rcp_f32_e32 v229, v229
	v_rcp_f32_e32 v230, v230
	v_rcp_f32_e32 v231, v231
	v_rcp_f32_e32 v232, v232
	v_rcp_f32_e32 v233, v233
	v_add_u32_e32 v249, 32, v142
	v_mad_i64_i32 v[220:221], s[22:23], v249, s90, v[216:217]
	v_pk_mul_f32 v[30:31], v[30:31], v[226:227]
	v_pk_mul_f32 v[32:33], v[32:33], v[228:229]
	v_pk_mul_f32 v[22:23], v[22:23], v[230:231]
	v_pk_mul_f32 v[24:25], v[24:25], v[232:233]
	v_lshl_add_u64 v[220:221], v[220:221], 0, v[218:219]
	v_cvt_pk_bf16_f32 v236, v30, v31
	v_cvt_pk_bf16_f32 v237, v32, v33
	v_cvt_pk_bf16_f32 v238, v22, v23
	v_cvt_pk_bf16_f32 v239, v24, v25
	global_store_dwordx4 v[220:221], v[236:239], off
	v_mul_f32_e32 v222, 0xbfb8aa3b, v248
	v_mul_f32_e32 v224, v248, v248
	v_pk_mul_f32 v[226:227], v[14:15], v[222:223] op_sel_hi:[1,0]
	v_pk_mul_f32 v[228:229], v[16:17], v[222:223] op_sel_hi:[1,0]
	v_pk_mul_f32 v[230:231], v[6:7], v[222:223] op_sel_hi:[1,0]
	v_pk_mul_f32 v[232:233], v[8:9], v[222:223] op_sel_hi:[1,0]
	v_pk_mul_f32 v[14:15], v[14:15], v[10:11]
	v_pk_mul_f32 v[16:17], v[16:17], v[12:13]
	v_pk_mul_f32 v[6:7], v[6:7], v[2:3]
	v_pk_mul_f32 v[8:9], v[8:9], v[4:5]
	v_exp_f32_e32 v226, v226
	v_exp_f32_e32 v227, v227
	v_exp_f32_e32 v228, v228
	v_exp_f32_e32 v229, v229
	v_exp_f32_e32 v230, v230
	v_exp_f32_e32 v231, v231
	v_exp_f32_e32 v232, v232
	v_exp_f32_e32 v233, v233
	v_pk_mul_f32 v[14:15], v[14:15], v[224:225] op_sel_hi:[1,0]
	v_pk_mul_f32 v[16:17], v[16:17], v[224:225] op_sel_hi:[1,0]
	v_pk_mul_f32 v[6:7], v[6:7], v[224:225] op_sel_hi:[1,0]
	v_pk_mul_f32 v[8:9], v[8:9], v[224:225] op_sel_hi:[1,0]
	v_pk_add_f32 v[226:227], v[226:227], v[234:235]
	v_pk_add_f32 v[228:229], v[228:229], v[234:235]
	v_pk_add_f32 v[230:231], v[230:231], v[234:235]
	v_pk_add_f32 v[232:233], v[232:233], v[234:235]
	v_rcp_f32_e32 v226, v226
	v_rcp_f32_e32 v227, v227
	v_rcp_f32_e32 v228, v228
	v_rcp_f32_e32 v229, v229
	v_rcp_f32_e32 v230, v230
	v_rcp_f32_e32 v231, v231
	v_rcp_f32_e32 v232, v232
	v_rcp_f32_e32 v233, v233
	v_add_u32_e32 v249, 48, v142
	v_mad_i64_i32 v[220:221], s[22:23], v249, s90, v[216:217]
	v_pk_mul_f32 v[14:15], v[14:15], v[226:227]
	v_pk_mul_f32 v[16:17], v[16:17], v[228:229]
	v_pk_mul_f32 v[6:7], v[6:7], v[230:231]
	v_pk_mul_f32 v[8:9], v[8:9], v[232:233]
	v_lshl_add_u64 v[220:221], v[220:221], 0, v[218:219]
	v_cvt_pk_bf16_f32 v236, v14, v15
	v_cvt_pk_bf16_f32 v237, v16, v17
	v_cvt_pk_bf16_f32 v238, v6, v7
	v_cvt_pk_bf16_f32 v239, v8, v9
	global_store_dwordx4 v[220:221], v[236:239], off
	s_mov_b32 s22, s54
	s_cbranch_vccnz .LBB0_455
